# pool rewrite + pipelined prep0 tile loop (1 barrier per tile, double-buffered LDS)
# speedup vs baseline: 1.0268x; 1.0033x over previous
.LBB0_5:
	s_or_b64 exec, exec, s[8:9]
	s_load_dwordx8 s[8:15], s[88:89], 0x0
	s_add_u32 s44, s88, 0xc8
	s_load_dwordx8 s[36:43], s[88:89], 0x20
	s_addc_u32 s45, s89, 0
	s_cmp_gt_i32 s2, -1
	s_waitcnt lgkmcnt(0)
	v_writelane_b32 v252, s8, 6
	s_cselect_b64 s[4:5], -1, 0
	s_cmp_lt_i32 s2, 0
	v_writelane_b32 v252, s9, 7
	v_writelane_b32 v252, s10, 8
	v_writelane_b32 v252, s11, 9
	v_writelane_b32 v252, s12, 10
	v_writelane_b32 v252, s13, 11
	v_writelane_b32 v252, s14, 12
	v_writelane_b32 v252, s15, 13
	v_writelane_b32 v252, s4, 14
	s_nop 1
	v_writelane_b32 v252, s5, 15
	s_cbranch_scc1 .LBB0_27
	s_load_dword s1, s[44:45], 0x11c
	v_mov_b32_e32 v11, v232
	s_waitcnt lgkmcnt(0)
	s_cmp_ge_i32 s2, s1
	v_lshlrev_b32_e32 v1, 3, v11
	s_cbranch_scc1 .LBB0_15
	s_load_dwordx2 s[8:9], s[88:89], 0x38
	s_load_dwordx2 s[10:11], s[88:89], 0x50
	s_load_dwordx2 s[12:13], s[88:89], 0x90
	v_lshrrev_b32_e32 v2, 3, v11
	v_and_b32_e32 v3, 56, v1
	v_mul_u32_u24_e32 v4, 0x3000, v2
	v_mul_u32_u24_e32 v5, 0x6080, v2
	v_lshlrev_b32_e32 v6, 14, v2
	v_mul_u32_u24_e32 v7, 0x104, v2
	v_lshl_add_u32 v7, v3, 2, v7
	v_mul_u32_u24_e32 v8, 0x104, v3
	v_lshl_add_u32 v8, v2, 2, v8
	v_lshlrev_b32_e32 v9, 11, v2
	v_lshl_add_u32 v9, v3, 1, v9
	v_add_u32_e32 v13, 0x4100, v7
	v_add_u32_e32 v14, 0x4100, v8
	v_add_u32_e32 v15, 0x400, v8
	v_add_u32_e32 v16, 0x400, v14
	s_waitcnt lgkmcnt(0)
	s_mov_b32 s22, s2
	s_cmp_ge_u32 s22, 0xc00
	s_cbranch_scc1 .Lp0_g1_1
	s_mul_i32 s14, s22, 2731
	s_lshr_b32 s14, s14, 21
	s_mul_i32 s15, s14, 768
	s_sub_u32 s15, s22, s15
	s_mul_i32 s16, s15, 1366
	s_lshr_b32 s16, s16, 16
	s_mul_i32 s17, s16, 48
	s_sub_u32 s17, s15, s17
	s_lshl_b32 s17, s17, 6
	s_lshl_b32 s16, s16, 6
	s_mul_i32 s18, s14, 0xc00000
	s_mul_i32 s19, s16, 0x3000
	s_add_u32 s18, s18, s19
	s_mul_i32 s3, s14, 0x600000
	s_add_u32 s14, s8, s18
	s_addc_u32 s15, s9, 0
	v_add_u32_e32 v10, s17, v3
	v_lshl_add_u32 v10, v10, 2, v4
	v_mov_b32_e32 v17, 1
	s_mul_i32 s18, s17, 0x800
	s_lshl_b32 s19, s16, 1
	s_add_u32 s18, s18, s19
	s_add_u32 s18, s18, s3
	s_add_u32 s18, s18, 0x3d00000
	s_add_u32 s20, s84, s18
	s_addc_u32 s21, s85, 0
	s_branch .Lp0_j_1
.Lp0_g1_1:
	s_cmp_ge_u32 s22, 0x1880
	s_cbranch_scc1 .Lp0_g2_1
	s_sub_u32 s15, s22, 0xc00
	s_cmp_ge_u32 s15, 1600
	s_cselect_b32 s14, 1, 0
	s_mul_i32 s16, s14, 1600
	s_sub_u32 s15, s15, s16
	s_mul_i32 s16, s15, 1311
	s_lshr_b32 s16, s16, 17
	s_mul_i32 s17, s16, 100
	s_sub_u32 s17, s15, s17
	s_lshl_b32 s17, s17, 6
	s_lshl_b32 s16, s16, 6
	s_mul_i32 s18, s14, 0x1820000
	s_mul_i32 s19, s16, 0x6080
	s_add_u32 s18, s18, s19
	s_mul_i32 s3, s14, 0xc80000
	s_add_u32 s14, s10, s18
	s_addc_u32 s15, s11, 0
	v_add_u32_e32 v10, s17, v3
	s_movk_i32 s19, 0x1820
	v_cmp_gt_i32_e64 s[18:19], s19, v10
	s_nop 1
	v_cndmask_b32_e64 v17, 0, 1, s[18:19]
	v_min_i32_e32 v10, 0x1818, v10
	v_lshl_add_u32 v10, v10, 2, v5
	s_mul_i32 s18, s17, 0x800
	s_lshl_b32 s19, s16, 1
	s_add_u32 s18, s18, s19
	s_add_u32 s18, s18, s3
	s_add_u32 s20, s84, s18
	s_addc_u32 s21, s85, 0
	s_branch .Lp0_j_1
.Lp0_g2_1:
	s_sub_u32 s15, s22, 0x1880
	s_lshr_b32 s14, s15, 10
	s_and_b32 s15, s15, 0x3ff
	s_lshr_b32 s16, s15, 6
	s_and_b32 s17, s15, 63
	s_lshl_b32 s17, s17, 6
	s_lshl_b32 s16, s16, 6
	s_lshl_b32 s18, s14, 24
	s_lshl_b32 s19, s16, 14
	s_add_u32 s18, s18, s19
	s_lshl_b32 s3, s14, 23
	s_add_u32 s14, s12, s18
	s_addc_u32 s15, s13, 0
	v_add_u32_e32 v10, s17, v3
	v_lshl_add_u32 v10, v10, 2, v6
	v_mov_b32_e32 v17, 1
	s_mul_i32 s18, s17, 0x800
	s_lshl_b32 s19, s16, 1
	s_add_u32 s18, s18, s19
	s_add_u32 s18, s18, s3
	s_add_u32 s18, s18, 0x2100000
	s_add_u32 s20, s84, s18
	s_addc_u32 s21, s85, 0
.Lp0_j_1:
	s_nop 4
	global_load_dwordx4 v[20:23], v10, s[14:15]
	global_load_dwordx4 v[24:27], v10, s[14:15] offset:16
	s_add_u32 s4, s22, 256
	s_cmp_ge_u32 s4, s1
	s_cselect_b32 s4, s2, s4
	s_cmp_ge_u32 s4, 0xc00
	s_cbranch_scc1 .Lp0_g1_2
	s_mul_i32 s14, s4, 2731
	s_lshr_b32 s14, s14, 21
	s_mul_i32 s15, s14, 768
	s_sub_u32 s15, s4, s15
	s_mul_i32 s16, s15, 1366
	s_lshr_b32 s16, s16, 16
	s_mul_i32 s17, s16, 48
	s_sub_u32 s17, s15, s17
	s_lshl_b32 s17, s17, 6
	s_lshl_b32 s16, s16, 6
	s_mul_i32 s18, s14, 0xc00000
	s_mul_i32 s19, s16, 0x3000
	s_add_u32 s18, s18, s19
	s_mul_i32 s3, s14, 0x600000
	s_add_u32 s14, s8, s18
	s_addc_u32 s15, s9, 0
	v_add_u32_e32 v12, s17, v3
	v_lshl_add_u32 v12, v12, 2, v4
	v_mov_b32_e32 v18, 1
	s_mul_i32 s18, s17, 0x800
	s_lshl_b32 s19, s16, 1
	s_add_u32 s18, s18, s19
	s_add_u32 s18, s18, s3
	s_add_u32 s18, s18, 0x3d00000
	s_add_u32 s24, s84, s18
	s_addc_u32 s25, s85, 0
	s_branch .Lp0_j_2
.Lp0_g1_2:
	s_cmp_ge_u32 s4, 0x1880
	s_cbranch_scc1 .Lp0_g2_2
	s_sub_u32 s15, s4, 0xc00
	s_cmp_ge_u32 s15, 1600
	s_cselect_b32 s14, 1, 0
	s_mul_i32 s16, s14, 1600
	s_sub_u32 s15, s15, s16
	s_mul_i32 s16, s15, 1311
	s_lshr_b32 s16, s16, 17
	s_mul_i32 s17, s16, 100
	s_sub_u32 s17, s15, s17
	s_lshl_b32 s17, s17, 6
	s_lshl_b32 s16, s16, 6
	s_mul_i32 s18, s14, 0x1820000
	s_mul_i32 s19, s16, 0x6080
	s_add_u32 s18, s18, s19
	s_mul_i32 s3, s14, 0xc80000
	s_add_u32 s14, s10, s18
	s_addc_u32 s15, s11, 0
	v_add_u32_e32 v12, s17, v3
	s_movk_i32 s19, 0x1820
	v_cmp_gt_i32_e64 s[18:19], s19, v12
	s_nop 1
	v_cndmask_b32_e64 v18, 0, 1, s[18:19]
	v_min_i32_e32 v12, 0x1818, v12
	v_lshl_add_u32 v12, v12, 2, v5
	s_mul_i32 s18, s17, 0x800
	s_lshl_b32 s19, s16, 1
	s_add_u32 s18, s18, s19
	s_add_u32 s18, s18, s3
	s_add_u32 s24, s84, s18
	s_addc_u32 s25, s85, 0
	s_branch .Lp0_j_2
.Lp0_g2_2:
	s_sub_u32 s15, s4, 0x1880
	s_lshr_b32 s14, s15, 10
	s_and_b32 s15, s15, 0x3ff
	s_lshr_b32 s16, s15, 6
	s_and_b32 s17, s15, 63
	s_lshl_b32 s17, s17, 6
	s_lshl_b32 s16, s16, 6
	s_lshl_b32 s18, s14, 24
	s_lshl_b32 s19, s16, 14
	s_add_u32 s18, s18, s19
	s_lshl_b32 s3, s14, 23
	s_add_u32 s14, s12, s18
	s_addc_u32 s15, s13, 0
	v_add_u32_e32 v12, s17, v3
	v_lshl_add_u32 v12, v12, 2, v6
	v_mov_b32_e32 v18, 1
	s_mul_i32 s18, s17, 0x800
	s_lshl_b32 s19, s16, 1
	s_add_u32 s18, s18, s19
	s_add_u32 s18, s18, s3
	s_add_u32 s18, s18, 0x2100000
	s_add_u32 s24, s84, s18
	s_addc_u32 s25, s85, 0
.Lp0_j_2:
	s_nop 4
	global_load_dwordx4 v[28:31], v12, s[14:15]
	global_load_dwordx4 v[32:35], v12, s[14:15] offset:16
	s_waitcnt vmcnt(2)
.Lp0_loop:
	v_cmp_ne_u32_e64 s[16:17], 0, v17
	s_nop 1
	v_cndmask_b32_e64 v20, 0, v20, s[16:17]
	v_cndmask_b32_e64 v21, 0, v21, s[16:17]
	v_cndmask_b32_e64 v22, 0, v22, s[16:17]
	v_cndmask_b32_e64 v23, 0, v23, s[16:17]
	v_cndmask_b32_e64 v24, 0, v24, s[16:17]
	v_cndmask_b32_e64 v25, 0, v25, s[16:17]
	v_cndmask_b32_e64 v26, 0, v26, s[16:17]
	v_cndmask_b32_e64 v27, 0, v27, s[16:17]
	ds_write2_b32 v7, v20, v21 offset0:0 offset1:1
	ds_write2_b32 v7, v22, v23 offset0:2 offset1:3
	ds_write2_b32 v7, v24, v25 offset0:4 offset1:5
	ds_write2_b32 v7, v26, v27 offset0:6 offset1:7
	s_waitcnt lgkmcnt(0)
	s_barrier
	ds_read2_b32 v[36:37], v8 offset1:65
	ds_read2_b32 v[38:39], v8 offset0:130 offset1:195
	ds_read2_b32 v[40:41], v15 offset0:4 offset1:69
	ds_read2_b32 v[42:43], v15 offset0:134 offset1:199
	s_waitcnt lgkmcnt(0)
	v_cvt_pk_bf16_f32 v44, v36, v37
	v_cvt_pk_bf16_f32 v45, v38, v39
	v_cvt_pk_bf16_f32 v46, v40, v41
	v_cvt_pk_bf16_f32 v47, v42, v43
	global_store_dwordx4 v9, v[44:47], s[20:21]
	s_add_u32 s4, s22, 512
	s_cmp_ge_u32 s4, s1
	s_cselect_b32 s4, s2, s4
	s_cmp_ge_u32 s4, 0xc00
	s_cbranch_scc1 .Lp0_g1_3
	s_mul_i32 s14, s4, 2731
	s_lshr_b32 s14, s14, 21
	s_mul_i32 s15, s14, 768
	s_sub_u32 s15, s4, s15
	s_mul_i32 s16, s15, 1366
	s_lshr_b32 s16, s16, 16
	s_mul_i32 s17, s16, 48
	s_sub_u32 s17, s15, s17
	s_lshl_b32 s17, s17, 6
	s_lshl_b32 s16, s16, 6
	s_mul_i32 s18, s14, 0xc00000
	s_mul_i32 s19, s16, 0x3000
	s_add_u32 s18, s18, s19
	s_mul_i32 s3, s14, 0x600000
	s_add_u32 s14, s8, s18
	s_addc_u32 s15, s9, 0
	v_add_u32_e32 v10, s17, v3
	v_lshl_add_u32 v10, v10, 2, v4
	v_mov_b32_e32 v17, 1
	s_mul_i32 s18, s17, 0x800
	s_lshl_b32 s19, s16, 1
	s_add_u32 s18, s18, s19
	s_add_u32 s18, s18, s3
	s_add_u32 s18, s18, 0x3d00000
	s_add_u32 s20, s84, s18
	s_addc_u32 s21, s85, 0
	s_branch .Lp0_j_3
.Lp0_g1_3:
	s_cmp_ge_u32 s4, 0x1880
	s_cbranch_scc1 .Lp0_g2_3
	s_sub_u32 s15, s4, 0xc00
	s_cmp_ge_u32 s15, 1600
	s_cselect_b32 s14, 1, 0
	s_mul_i32 s16, s14, 1600
	s_sub_u32 s15, s15, s16
	s_mul_i32 s16, s15, 1311
	s_lshr_b32 s16, s16, 17
	s_mul_i32 s17, s16, 100
	s_sub_u32 s17, s15, s17
	s_lshl_b32 s17, s17, 6
	s_lshl_b32 s16, s16, 6
	s_mul_i32 s18, s14, 0x1820000
	s_mul_i32 s19, s16, 0x6080
	s_add_u32 s18, s18, s19
	s_mul_i32 s3, s14, 0xc80000
	s_add_u32 s14, s10, s18
	s_addc_u32 s15, s11, 0
	v_add_u32_e32 v10, s17, v3
	s_movk_i32 s19, 0x1820
	v_cmp_gt_i32_e64 s[18:19], s19, v10
	s_nop 1
	v_cndmask_b32_e64 v17, 0, 1, s[18:19]
	v_min_i32_e32 v10, 0x1818, v10
	v_lshl_add_u32 v10, v10, 2, v5
	s_mul_i32 s18, s17, 0x800
	s_lshl_b32 s19, s16, 1
	s_add_u32 s18, s18, s19
	s_add_u32 s18, s18, s3
	s_add_u32 s20, s84, s18
	s_addc_u32 s21, s85, 0
	s_branch .Lp0_j_3
.Lp0_g2_3:
	s_sub_u32 s15, s4, 0x1880
	s_lshr_b32 s14, s15, 10
	s_and_b32 s15, s15, 0x3ff
	s_lshr_b32 s16, s15, 6
	s_and_b32 s17, s15, 63
	s_lshl_b32 s17, s17, 6
	s_lshl_b32 s16, s16, 6
	s_lshl_b32 s18, s14, 24
	s_lshl_b32 s19, s16, 14
	s_add_u32 s18, s18, s19
	s_lshl_b32 s3, s14, 23
	s_add_u32 s14, s12, s18
	s_addc_u32 s15, s13, 0
	v_add_u32_e32 v10, s17, v3
	v_lshl_add_u32 v10, v10, 2, v6
	v_mov_b32_e32 v17, 1
	s_mul_i32 s18, s17, 0x800
	s_lshl_b32 s19, s16, 1
	s_add_u32 s18, s18, s19
	s_add_u32 s18, s18, s3
	s_add_u32 s18, s18, 0x2100000
	s_add_u32 s20, s84, s18
	s_addc_u32 s21, s85, 0
.Lp0_j_3:
	s_nop 4
	global_load_dwordx4 v[20:23], v10, s[14:15]
	global_load_dwordx4 v[24:27], v10, s[14:15] offset:16
	s_waitcnt vmcnt(3)
	s_add_u32 s4, s22, 256
	s_cmp_ge_u32 s4, s1
	s_cbranch_scc1 .Lp0_end
	v_cmp_ne_u32_e64 s[16:17], 0, v18
	s_nop 1
	v_cndmask_b32_e64 v28, 0, v28, s[16:17]
	v_cndmask_b32_e64 v29, 0, v29, s[16:17]
	v_cndmask_b32_e64 v30, 0, v30, s[16:17]
	v_cndmask_b32_e64 v31, 0, v31, s[16:17]
	v_cndmask_b32_e64 v32, 0, v32, s[16:17]
	v_cndmask_b32_e64 v33, 0, v33, s[16:17]
	v_cndmask_b32_e64 v34, 0, v34, s[16:17]
	v_cndmask_b32_e64 v35, 0, v35, s[16:17]
	ds_write2_b32 v13, v28, v29 offset0:0 offset1:1
	ds_write2_b32 v13, v30, v31 offset0:2 offset1:3
	ds_write2_b32 v13, v32, v33 offset0:4 offset1:5
	ds_write2_b32 v13, v34, v35 offset0:6 offset1:7
	s_waitcnt lgkmcnt(0)
	s_barrier
	ds_read2_b32 v[36:37], v14 offset1:65
	ds_read2_b32 v[38:39], v14 offset0:130 offset1:195
	ds_read2_b32 v[40:41], v16 offset0:4 offset1:69
	ds_read2_b32 v[42:43], v16 offset0:134 offset1:199
	s_waitcnt lgkmcnt(0)
	v_cvt_pk_bf16_f32 v52, v36, v37
	v_cvt_pk_bf16_f32 v53, v38, v39
	v_cvt_pk_bf16_f32 v54, v40, v41
	v_cvt_pk_bf16_f32 v55, v42, v43
	global_store_dwordx4 v9, v[52:55], s[24:25]
	s_add_u32 s4, s22, 768
	s_cmp_ge_u32 s4, s1
	s_cselect_b32 s4, s2, s4
	s_cmp_ge_u32 s4, 0xc00
	s_cbranch_scc1 .Lp0_g1_4
	s_mul_i32 s14, s4, 2731
	s_lshr_b32 s14, s14, 21
	s_mul_i32 s15, s14, 768
	s_sub_u32 s15, s4, s15
	s_mul_i32 s16, s15, 1366
	s_lshr_b32 s16, s16, 16
	s_mul_i32 s17, s16, 48
	s_sub_u32 s17, s15, s17
	s_lshl_b32 s17, s17, 6
	s_lshl_b32 s16, s16, 6
	s_mul_i32 s18, s14, 0xc00000
	s_mul_i32 s19, s16, 0x3000
	s_add_u32 s18, s18, s19
	s_mul_i32 s3, s14, 0x600000
	s_add_u32 s14, s8, s18
	s_addc_u32 s15, s9, 0
	v_add_u32_e32 v12, s17, v3
	v_lshl_add_u32 v12, v12, 2, v4
	v_mov_b32_e32 v18, 1
	s_mul_i32 s18, s17, 0x800
	s_lshl_b32 s19, s16, 1
	s_add_u32 s18, s18, s19
	s_add_u32 s18, s18, s3
	s_add_u32 s18, s18, 0x3d00000
	s_add_u32 s24, s84, s18
	s_addc_u32 s25, s85, 0
	s_branch .Lp0_j_4

.Lp0_j_4:
	s_nop 4
	global_load_dwordx4 v[28:31], v12, s[14:15]
	global_load_dwordx4 v[32:35], v12, s[14:15] offset:16
	s_waitcnt vmcnt(3)
	s_add_u32 s22, s22, 512
	s_cmp_lt_u32 s22, s1
	s_cbranch_scc1 .Lp0_loop
.Lp0_end:
	s_waitcnt vmcnt(0)
	s_barrier

.LBB0_663:
	s_or_b64 exec, exec, s[0:1]
	v_readlane_b32 s6, v255, 10
	v_readlane_b32 s7, v255, 11
	s_mov_b64 s[0:1], -1
	s_and_b64 vcc, exec, s[6:7]
	s_waitcnt lgkmcnt(0)
	s_barrier
	s_cbranch_vccz .LBB0_717
	v_mov_b32_e32 v0, v232
	v_readlane_b32 s0, v254, 17
	s_lshl_b32 s21, s50, 7
	s_nop 0
	v_add_u32_e32 v96, s0, v0
	s_mov_b32 s0, 0x28000
	v_cmp_gt_i32_e32 vcc, s0, v96
	v_readlane_b32 s0, v254, 56
	s_nop 1
	v_lshl_add_u32 v97, v0, 3, s0
	s_and_saveexec_b64 s[6:7], vcc
	s_cbranch_execz .LBB0_705
	v_and_b32_e32 v48, 0xff, v96
	v_readfirstlane_b32 s49, v96
	v_lshlrev_b32_e32 v114, 5, v48
	v_lshlrev_b32_e32 v48, 4, v48
	s_nop 3
	s_bfe_u32 s0, s49, 0x20006
	s_lshl_b32 s41, 2, s0
	s_add_i32 s43, s41, -1
	s_bfe_u32 s0, s49, 0x60008
	s_lshl_b32 s40, s0, 5
	s_lshr_b32 s1, s49, 14
	s_lshl_b32 s42, s1, 11
	s_add_i32 s48, s40, 32
	s_add_i32 s0, s42, s40
	s_lshl_b32 s0, s0, 12
	s_add_u32 s22, s70, s0
	s_addc_u32 s23, s71, 0
	v_mov_b32_e32 v32, 0
	v_mov_b32_e32 v33, 0
	v_mov_b32_e32 v34, 0
	v_mov_b32_e32 v35, 0
	v_mov_b32_e32 v36, 0
	v_mov_b32_e32 v37, 0
	v_mov_b32_e32 v38, 0
	v_mov_b32_e32 v39, 0
	s_add_i32 s0, s42, s40
	s_lshl_b32 s0, s0, 13
	s_add_u32 s8, s4, s0
	s_addc_u32 s9, s5, 0
	global_load_dwordx4 v[0:3], v48, s[8:9]
	s_add_u32 s8, s8, 0x2000
	s_addc_u32 s9, s9, 0
	global_load_dwordx4 v[4:7], v48, s[8:9]
	s_add_u32 s8, s8, 0x2000
	s_addc_u32 s9, s9, 0
	global_load_dwordx4 v[8:11], v48, s[8:9]
	s_add_u32 s8, s8, 0x2000
	s_addc_u32 s9, s9, 0
	global_load_dwordx4 v[12:15], v48, s[8:9]
	s_sub_i32 s1, s40, s43
	s_add_i32 s0, s1, 0
	s_max_i32 s0, s0, 0
	s_add_i32 s0, s0, s42
	s_lshl_b32 s0, s0, 13
	s_add_u32 s10, s4, s0
	s_addc_u32 s11, s5, 0
	global_load_dwordx4 v[16:19], v48, s[10:11]
	s_add_i32 s0, s1, 1
	s_max_i32 s0, s0, 0
	s_add_i32 s0, s0, s42
	s_lshl_b32 s0, s0, 13
	s_add_u32 s10, s4, s0
	s_addc_u32 s11, s5, 0
	global_load_dwordx4 v[20:23], v48, s[10:11]
	s_add_i32 s0, s1, 2
	s_max_i32 s0, s0, 0
	s_add_i32 s0, s0, s42
	s_lshl_b32 s0, s0, 13
	s_add_u32 s10, s4, s0
	s_addc_u32 s11, s5, 0
	global_load_dwordx4 v[24:27], v48, s[10:11]
	s_add_i32 s0, s1, 3
	s_max_i32 s0, s0, 0
	s_add_i32 s0, s0, s42
	s_lshl_b32 s0, s0, 13
	s_add_u32 s10, s4, s0
	s_addc_u32 s11, s5, 0
	global_load_dwordx4 v[28:31], v48, s[10:11]
	s_add_i32 s47, s40, 4
	s_add_i32 s0, s42, s47
	s_lshl_b32 s0, s0, 13
	s_add_u32 s8, s4, s0
	s_addc_u32 s9, s5, 0
	global_load_dwordx4 v[50:53], v48, s[8:9]
	s_add_u32 s8, s8, 0x2000
	s_addc_u32 s9, s9, 0
	global_load_dwordx4 v[54:57], v48, s[8:9]
	s_add_u32 s8, s8, 0x2000
	s_addc_u32 s9, s9, 0
	global_load_dwordx4 v[58:61], v48, s[8:9]
	s_add_u32 s8, s8, 0x2000
	s_addc_u32 s9, s9, 0
	global_load_dwordx4 v[62:65], v48, s[8:9]
	s_sub_i32 s1, s47, s43
	s_add_i32 s0, s1, 0
	s_max_i32 s0, s0, 0
	s_add_i32 s0, s0, s42
	s_lshl_b32 s0, s0, 13
	s_add_u32 s10, s4, s0
	s_addc_u32 s11, s5, 0
	global_load_dwordx4 v[66:69], v48, s[10:11]
	s_add_i32 s0, s1, 1
	s_max_i32 s0, s0, 0
	s_add_i32 s0, s0, s42
	s_lshl_b32 s0, s0, 13
	s_add_u32 s10, s4, s0
	s_addc_u32 s11, s5, 0
	global_load_dwordx4 v[70:73], v48, s[10:11]
	s_add_i32 s0, s1, 2
	s_max_i32 s0, s0, 0
	s_add_i32 s0, s0, s42
	s_lshl_b32 s0, s0, 13
	s_add_u32 s10, s4, s0
	s_addc_u32 s11, s5, 0
	global_load_dwordx4 v[74:77], v48, s[10:11]
	s_add_i32 s0, s1, 3
	s_max_i32 s0, s0, 0
	s_add_i32 s0, s0, s42
	s_lshl_b32 s0, s0, 13
	s_add_u32 s10, s4, s0
	s_addc_u32 s11, s5, 0
	global_load_dwordx4 v[78:81], v48, s[10:11]
	s_cmp_lg_u32 s41, 16
	s_cbranch_scc1 .Lpl_nox_1
	s_cmp_eq_u32 s48, 32
	s_cbranch_scc1 .Lpl_nox_1
	s_add_i32 s0, s42, s40
	s_lshl_b32 s0, s0, 13
	s_add_u32 s8, s4, s0
	s_addc_u32 s9, s5, 0
	s_sub_u32 s8, s8, 0x2000
	s_subb_u32 s9, s9, 0
	global_load_dwordx4 v[40:43], v48, s[8:9]
	s_sub_u32 s8, s8, 0x2000
	s_subb_u32 s9, s9, 0
	global_load_dwordx4 v[44:47], v48, s[8:9]
	s_sub_u32 s8, s8, 0x2000
	s_subb_u32 s9, s9, 0
	global_load_dwordx4 v[82:85], v48, s[8:9]
	s_sub_u32 s8, s8, 0x2000
	s_subb_u32 s9, s9, 0
	global_load_dwordx4 v[86:89], v48, s[8:9]
	s_sub_u32 s8, s8, 0x2000
	s_subb_u32 s9, s9, 0
	global_load_dwordx4 v[90:93], v48, s[8:9]
	s_sub_u32 s8, s8, 0x2000
	s_subb_u32 s9, s9, 0
	global_load_dwordx4 v[98:101], v48, s[8:9]
	s_sub_u32 s8, s8, 0x2000
	s_subb_u32 s9, s9, 0
	global_load_dwordx4 v[102:105], v48, s[8:9]
.Lpl_nox_1:
	s_waitcnt vmcnt(0)
	s_cmp_eq_u32 s48, 32
	s_cbranch_scc1 .Lpl_wdone_2
	s_cmp_eq_u32 s41, 4
	s_cbranch_scc1 .Lpl_w4_3
	s_cmp_eq_u32 s41, 8
	s_cbranch_scc1 .Lpl_w8_4
	s_cmp_eq_u32 s41, 16
	s_cbranch_scc1 .Lpl_w16_5
	v_lshlrev_b32_e32 v106, 16, v16
	v_and_b32_e32 v107, 0xffff0000, v16
	v_lshlrev_b32_e32 v108, 16, v17
	v_and_b32_e32 v109, 0xffff0000, v17
	v_lshlrev_b32_e32 v110, 16, v18
	v_and_b32_e32 v111, 0xffff0000, v18
	v_lshlrev_b32_e32 v112, 16, v19
	v_and_b32_e32 v113, 0xffff0000, v19
	v_pk_add_f32 v[32:33], v[32:33], v[106:107]
	v_pk_add_f32 v[34:35], v[34:35], v[108:109]
	v_pk_add_f32 v[36:37], v[36:37], v[110:111]
	v_pk_add_f32 v[38:39], v[38:39], v[112:113]
	s_branch .Lpl_wdone_2

.Lpl_wdone_2:
.Lpl_loop_6:
	s_add_i32 s0, s40, 1
	s_min_i32 s0, s0, s41
	v_cvt_f32_u32_e32 v98, s0
	v_div_scale_f32 v99, s[10:11], v98, v98, 1.0
	v_rcp_f32_e32 v100, v99
	s_nop 0
	v_fma_f32 v101, -v99, v100, 1.0
	v_fmac_f32_e32 v100, v101, v100
	v_div_scale_f32 v101, vcc, 1.0, v98, 1.0
	v_mul_f32_e32 v102, v101, v100
	v_fma_f32 v103, -v99, v102, v101
	v_fmac_f32_e32 v102, v103, v100
	v_fma_f32 v99, -v99, v102, v101
	v_div_fmas_f32 v99, v99, v100, v102
	v_div_fixup_f32 v94, v99, v98, 1.0
	v_mov_b32_e32 v95, v94
	v_lshlrev_b32_e32 v40, 16, v0
	v_and_b32_e32 v41, 0xffff0000, v0
	v_lshlrev_b32_e32 v42, 16, v1
	v_and_b32_e32 v43, 0xffff0000, v1
	v_lshlrev_b32_e32 v44, 16, v2
	v_and_b32_e32 v45, 0xffff0000, v2
	v_lshlrev_b32_e32 v46, 16, v3
	v_and_b32_e32 v47, 0xffff0000, v3
	v_pk_add_f32 v[32:33], v[32:33], v[40:41]
	v_pk_add_f32 v[34:35], v[34:35], v[42:43]
	v_pk_add_f32 v[36:37], v[36:37], v[44:45]
	v_pk_add_f32 v[38:39], v[38:39], v[46:47]
	v_pk_fma_f32 v[82:83], v[32:33], v[94:95], v[40:41] neg_lo:[0,0,1] neg_hi:[0,0,1]
	v_pk_fma_f32 v[84:85], v[34:35], v[94:95], v[42:43] neg_lo:[0,0,1] neg_hi:[0,0,1]
	v_pk_fma_f32 v[86:87], v[36:37], v[94:95], v[44:45] neg_lo:[0,0,1] neg_hi:[0,0,1]
	v_pk_fma_f32 v[88:89], v[38:39], v[94:95], v[46:47] neg_lo:[0,0,1] neg_hi:[0,0,1]
	v_cvt_pk_bf16_f32 v90, v82, v83
	v_cvt_pk_bf16_f32 v91, v84, v85
	v_cvt_pk_bf16_f32 v92, v86, v87
	v_cvt_pk_bf16_f32 v93, v88, v89
	global_store_dwordx4 v48, v[90:93], s[22:23]
	s_add_u32 s22, s22, 0x1000
	s_addc_u32 s23, s23, 0
	s_add_i32 s0, s40, 0
	s_cmp_lt_i32 s0, s43
	s_cbranch_scc1 .Lpl_sk_7
	v_lshlrev_b32_e32 v82, 16, v16
	v_and_b32_e32 v83, 0xffff0000, v16
	v_lshlrev_b32_e32 v84, 16, v17
	v_and_b32_e32 v85, 0xffff0000, v17
	v_lshlrev_b32_e32 v86, 16, v18
	v_and_b32_e32 v87, 0xffff0000, v18
	v_lshlrev_b32_e32 v88, 16, v19
	v_and_b32_e32 v89, 0xffff0000, v19
	v_pk_add_f32 v[32:33], v[32:33], v[82:83] neg_lo:[0,1] neg_hi:[0,1]
	v_pk_add_f32 v[34:35], v[34:35], v[84:85] neg_lo:[0,1] neg_hi:[0,1]
	v_pk_add_f32 v[36:37], v[36:37], v[86:87] neg_lo:[0,1] neg_hi:[0,1]
	v_pk_add_f32 v[38:39], v[38:39], v[88:89] neg_lo:[0,1] neg_hi:[0,1]
.Lpl_sk_7:
	s_add_i32 s0, s40, 2
	s_min_i32 s0, s0, s41
	v_cvt_f32_u32_e32 v98, s0
	v_div_scale_f32 v99, s[10:11], v98, v98, 1.0
	v_rcp_f32_e32 v100, v99
	s_nop 0
	v_fma_f32 v101, -v99, v100, 1.0
	v_fmac_f32_e32 v100, v101, v100
	v_div_scale_f32 v101, vcc, 1.0, v98, 1.0
	v_mul_f32_e32 v102, v101, v100
	v_fma_f32 v103, -v99, v102, v101
	v_fmac_f32_e32 v102, v103, v100
	v_fma_f32 v99, -v99, v102, v101
	v_div_fmas_f32 v99, v99, v100, v102
	v_div_fixup_f32 v94, v99, v98, 1.0
	v_mov_b32_e32 v95, v94
	v_lshlrev_b32_e32 v40, 16, v4
	v_and_b32_e32 v41, 0xffff0000, v4
	v_lshlrev_b32_e32 v42, 16, v5
	v_and_b32_e32 v43, 0xffff0000, v5
	v_lshlrev_b32_e32 v44, 16, v6
	v_and_b32_e32 v45, 0xffff0000, v6
	v_lshlrev_b32_e32 v46, 16, v7
	v_and_b32_e32 v47, 0xffff0000, v7
	v_pk_add_f32 v[32:33], v[32:33], v[40:41]
	v_pk_add_f32 v[34:35], v[34:35], v[42:43]
	v_pk_add_f32 v[36:37], v[36:37], v[44:45]
	v_pk_add_f32 v[38:39], v[38:39], v[46:47]
	v_pk_fma_f32 v[82:83], v[32:33], v[94:95], v[40:41] neg_lo:[0,0,1] neg_hi:[0,0,1]
	v_pk_fma_f32 v[84:85], v[34:35], v[94:95], v[42:43] neg_lo:[0,0,1] neg_hi:[0,0,1]
	v_pk_fma_f32 v[86:87], v[36:37], v[94:95], v[44:45] neg_lo:[0,0,1] neg_hi:[0,0,1]
	v_pk_fma_f32 v[88:89], v[38:39], v[94:95], v[46:47] neg_lo:[0,0,1] neg_hi:[0,0,1]
	v_cvt_pk_bf16_f32 v90, v82, v83
	v_cvt_pk_bf16_f32 v91, v84, v85
	v_cvt_pk_bf16_f32 v92, v86, v87
	v_cvt_pk_bf16_f32 v93, v88, v89
	global_store_dwordx4 v48, v[90:93], s[22:23]
	s_add_u32 s22, s22, 0x1000
	s_addc_u32 s23, s23, 0
	s_add_i32 s0, s40, 1
	s_cmp_lt_i32 s0, s43
	s_cbranch_scc1 .Lpl_sk_8
	v_lshlrev_b32_e32 v82, 16, v20
	v_and_b32_e32 v83, 0xffff0000, v20
	v_lshlrev_b32_e32 v84, 16, v21
	v_and_b32_e32 v85, 0xffff0000, v21
	v_lshlrev_b32_e32 v86, 16, v22
	v_and_b32_e32 v87, 0xffff0000, v22
	v_lshlrev_b32_e32 v88, 16, v23
	v_and_b32_e32 v89, 0xffff0000, v23
	v_pk_add_f32 v[32:33], v[32:33], v[82:83] neg_lo:[0,1] neg_hi:[0,1]
	v_pk_add_f32 v[34:35], v[34:35], v[84:85] neg_lo:[0,1] neg_hi:[0,1]
	v_pk_add_f32 v[36:37], v[36:37], v[86:87] neg_lo:[0,1] neg_hi:[0,1]
	v_pk_add_f32 v[38:39], v[38:39], v[88:89] neg_lo:[0,1] neg_hi:[0,1]
.Lpl_sk_8:
	s_add_i32 s0, s40, 3
	s_min_i32 s0, s0, s41
	v_cvt_f32_u32_e32 v98, s0
	v_div_scale_f32 v99, s[10:11], v98, v98, 1.0
	v_rcp_f32_e32 v100, v99
	s_nop 0
	v_fma_f32 v101, -v99, v100, 1.0
	v_fmac_f32_e32 v100, v101, v100
	v_div_scale_f32 v101, vcc, 1.0, v98, 1.0
	v_mul_f32_e32 v102, v101, v100
	v_fma_f32 v103, -v99, v102, v101
	v_fmac_f32_e32 v102, v103, v100
	v_fma_f32 v99, -v99, v102, v101
	v_div_fmas_f32 v99, v99, v100, v102
	v_div_fixup_f32 v94, v99, v98, 1.0
	v_mov_b32_e32 v95, v94
	v_lshlrev_b32_e32 v40, 16, v8
	v_and_b32_e32 v41, 0xffff0000, v8
	v_lshlrev_b32_e32 v42, 16, v9
	v_and_b32_e32 v43, 0xffff0000, v9
	v_lshlrev_b32_e32 v44, 16, v10
	v_and_b32_e32 v45, 0xffff0000, v10
	v_lshlrev_b32_e32 v46, 16, v11
	v_and_b32_e32 v47, 0xffff0000, v11
	v_pk_add_f32 v[32:33], v[32:33], v[40:41]
	v_pk_add_f32 v[34:35], v[34:35], v[42:43]
	v_pk_add_f32 v[36:37], v[36:37], v[44:45]
	v_pk_add_f32 v[38:39], v[38:39], v[46:47]
	v_pk_fma_f32 v[82:83], v[32:33], v[94:95], v[40:41] neg_lo:[0,0,1] neg_hi:[0,0,1]
	v_pk_fma_f32 v[84:85], v[34:35], v[94:95], v[42:43] neg_lo:[0,0,1] neg_hi:[0,0,1]
	v_pk_fma_f32 v[86:87], v[36:37], v[94:95], v[44:45] neg_lo:[0,0,1] neg_hi:[0,0,1]
	v_pk_fma_f32 v[88:89], v[38:39], v[94:95], v[46:47] neg_lo:[0,0,1] neg_hi:[0,0,1]
	v_cvt_pk_bf16_f32 v90, v82, v83
	v_cvt_pk_bf16_f32 v91, v84, v85
	v_cvt_pk_bf16_f32 v92, v86, v87
	v_cvt_pk_bf16_f32 v93, v88, v89
	global_store_dwordx4 v48, v[90:93], s[22:23]
	s_add_u32 s22, s22, 0x1000
	s_addc_u32 s23, s23, 0
	s_add_i32 s0, s40, 2
	s_cmp_lt_i32 s0, s43
	s_cbranch_scc1 .Lpl_sk_9
	v_lshlrev_b32_e32 v82, 16, v24
	v_and_b32_e32 v83, 0xffff0000, v24
	v_lshlrev_b32_e32 v84, 16, v25
	v_and_b32_e32 v85, 0xffff0000, v25
	v_lshlrev_b32_e32 v86, 16, v26
	v_and_b32_e32 v87, 0xffff0000, v26
	v_lshlrev_b32_e32 v88, 16, v27
	v_and_b32_e32 v89, 0xffff0000, v27
	v_pk_add_f32 v[32:33], v[32:33], v[82:83] neg_lo:[0,1] neg_hi:[0,1]
	v_pk_add_f32 v[34:35], v[34:35], v[84:85] neg_lo:[0,1] neg_hi:[0,1]
	v_pk_add_f32 v[36:37], v[36:37], v[86:87] neg_lo:[0,1] neg_hi:[0,1]
	v_pk_add_f32 v[38:39], v[38:39], v[88:89] neg_lo:[0,1] neg_hi:[0,1]
.Lpl_sk_9:
	s_add_i32 s0, s40, 4
	s_min_i32 s0, s0, s41
	v_cvt_f32_u32_e32 v98, s0
	v_div_scale_f32 v99, s[10:11], v98, v98, 1.0
	v_rcp_f32_e32 v100, v99
	s_nop 0
	v_fma_f32 v101, -v99, v100, 1.0
	v_fmac_f32_e32 v100, v101, v100
	v_div_scale_f32 v101, vcc, 1.0, v98, 1.0
	v_mul_f32_e32 v102, v101, v100
	v_fma_f32 v103, -v99, v102, v101
	v_fmac_f32_e32 v102, v103, v100
	v_fma_f32 v99, -v99, v102, v101
	v_div_fmas_f32 v99, v99, v100, v102
	v_div_fixup_f32 v94, v99, v98, 1.0
	v_mov_b32_e32 v95, v94
	v_lshlrev_b32_e32 v40, 16, v12
	v_and_b32_e32 v41, 0xffff0000, v12
	v_lshlrev_b32_e32 v42, 16, v13
	v_and_b32_e32 v43, 0xffff0000, v13
	v_lshlrev_b32_e32 v44, 16, v14
	v_and_b32_e32 v45, 0xffff0000, v14
	v_lshlrev_b32_e32 v46, 16, v15
	v_and_b32_e32 v47, 0xffff0000, v15
	v_pk_add_f32 v[32:33], v[32:33], v[40:41]
	v_pk_add_f32 v[34:35], v[34:35], v[42:43]
	v_pk_add_f32 v[36:37], v[36:37], v[44:45]
	v_pk_add_f32 v[38:39], v[38:39], v[46:47]
	v_pk_fma_f32 v[82:83], v[32:33], v[94:95], v[40:41] neg_lo:[0,0,1] neg_hi:[0,0,1]
	v_pk_fma_f32 v[84:85], v[34:35], v[94:95], v[42:43] neg_lo:[0,0,1] neg_hi:[0,0,1]
	v_pk_fma_f32 v[86:87], v[36:37], v[94:95], v[44:45] neg_lo:[0,0,1] neg_hi:[0,0,1]
	v_pk_fma_f32 v[88:89], v[38:39], v[94:95], v[46:47] neg_lo:[0,0,1] neg_hi:[0,0,1]
	v_cvt_pk_bf16_f32 v90, v82, v83
	v_cvt_pk_bf16_f32 v91, v84, v85
	v_cvt_pk_bf16_f32 v92, v86, v87
	v_cvt_pk_bf16_f32 v93, v88, v89
	global_store_dwordx4 v48, v[90:93], s[22:23]
	s_add_u32 s22, s22, 0x1000
	s_addc_u32 s23, s23, 0
	s_add_i32 s0, s40, 3
	s_cmp_lt_i32 s0, s43
	s_cbranch_scc1 .Lpl_sk_10
	v_lshlrev_b32_e32 v82, 16, v28
	v_and_b32_e32 v83, 0xffff0000, v28
	v_lshlrev_b32_e32 v84, 16, v29
	v_and_b32_e32 v85, 0xffff0000, v29
	v_lshlrev_b32_e32 v86, 16, v30
	v_and_b32_e32 v87, 0xffff0000, v30
	v_lshlrev_b32_e32 v88, 16, v31
	v_and_b32_e32 v89, 0xffff0000, v31
	v_pk_add_f32 v[32:33], v[32:33], v[82:83] neg_lo:[0,1] neg_hi:[0,1]
	v_pk_add_f32 v[34:35], v[34:35], v[84:85] neg_lo:[0,1] neg_hi:[0,1]
	v_pk_add_f32 v[36:37], v[36:37], v[86:87] neg_lo:[0,1] neg_hi:[0,1]
	v_pk_add_f32 v[38:39], v[38:39], v[88:89] neg_lo:[0,1] neg_hi:[0,1]
.Lpl_sk_10:
	s_add_i32 s46, s40, 8
	s_add_i32 s0, s48, -4
	s_min_i32 s46, s46, s0
	s_add_i32 s0, s42, s46
	s_lshl_b32 s0, s0, 13
	s_add_u32 s8, s4, s0
	s_addc_u32 s9, s5, 0
	global_load_dwordx4 v[0:3], v48, s[8:9]
	s_add_u32 s8, s8, 0x2000
	s_addc_u32 s9, s9, 0
	global_load_dwordx4 v[4:7], v48, s[8:9]
	s_add_u32 s8, s8, 0x2000
	s_addc_u32 s9, s9, 0
	global_load_dwordx4 v[8:11], v48, s[8:9]
	s_add_u32 s8, s8, 0x2000
	s_addc_u32 s9, s9, 0
	global_load_dwordx4 v[12:15], v48, s[8:9]
	s_sub_i32 s1, s46, s43
	s_add_i32 s0, s1, 0
	s_max_i32 s0, s0, 0
	s_add_i32 s0, s0, s42
	s_lshl_b32 s0, s0, 13
	s_add_u32 s10, s4, s0
	s_addc_u32 s11, s5, 0
	global_load_dwordx4 v[16:19], v48, s[10:11]
	s_add_i32 s0, s1, 1
	s_max_i32 s0, s0, 0
	s_add_i32 s0, s0, s42
	s_lshl_b32 s0, s0, 13
	s_add_u32 s10, s4, s0
	s_addc_u32 s11, s5, 0
	global_load_dwordx4 v[20:23], v48, s[10:11]
	s_add_i32 s0, s1, 2
	s_max_i32 s0, s0, 0
	s_add_i32 s0, s0, s42
	s_lshl_b32 s0, s0, 13
	s_add_u32 s10, s4, s0
	s_addc_u32 s11, s5, 0
	global_load_dwordx4 v[24:27], v48, s[10:11]
	s_add_i32 s0, s1, 3
	s_max_i32 s0, s0, 0
	s_add_i32 s0, s0, s42
	s_lshl_b32 s0, s0, 13
	s_add_u32 s10, s4, s0
	s_addc_u32 s11, s5, 0
	global_load_dwordx4 v[28:31], v48, s[10:11]
	s_waitcnt vmcnt(12)
	s_add_i32 s47, s40, 4
	s_add_i32 s0, s47, 1
	s_min_i32 s0, s0, s41
	v_cvt_f32_u32_e32 v98, s0
	v_div_scale_f32 v99, s[10:11], v98, v98, 1.0
	v_rcp_f32_e32 v100, v99
	s_nop 0
	v_fma_f32 v101, -v99, v100, 1.0
	v_fmac_f32_e32 v100, v101, v100
	v_div_scale_f32 v101, vcc, 1.0, v98, 1.0
	v_mul_f32_e32 v102, v101, v100
	v_fma_f32 v103, -v99, v102, v101
	v_fmac_f32_e32 v102, v103, v100
	v_fma_f32 v99, -v99, v102, v101
	v_div_fmas_f32 v99, v99, v100, v102
	v_div_fixup_f32 v94, v99, v98, 1.0
	v_mov_b32_e32 v95, v94
	v_lshlrev_b32_e32 v40, 16, v50
	v_and_b32_e32 v41, 0xffff0000, v50
	v_lshlrev_b32_e32 v42, 16, v51
	v_and_b32_e32 v43, 0xffff0000, v51
	v_lshlrev_b32_e32 v44, 16, v52
	v_and_b32_e32 v45, 0xffff0000, v52
	v_lshlrev_b32_e32 v46, 16, v53
	v_and_b32_e32 v47, 0xffff0000, v53
	v_pk_add_f32 v[32:33], v[32:33], v[40:41]
	v_pk_add_f32 v[34:35], v[34:35], v[42:43]
	v_pk_add_f32 v[36:37], v[36:37], v[44:45]
	v_pk_add_f32 v[38:39], v[38:39], v[46:47]
	v_pk_fma_f32 v[82:83], v[32:33], v[94:95], v[40:41] neg_lo:[0,0,1] neg_hi:[0,0,1]
	v_pk_fma_f32 v[84:85], v[34:35], v[94:95], v[42:43] neg_lo:[0,0,1] neg_hi:[0,0,1]
	v_pk_fma_f32 v[86:87], v[36:37], v[94:95], v[44:45] neg_lo:[0,0,1] neg_hi:[0,0,1]
	v_pk_fma_f32 v[88:89], v[38:39], v[94:95], v[46:47] neg_lo:[0,0,1] neg_hi:[0,0,1]
	v_cvt_pk_bf16_f32 v90, v82, v83
	v_cvt_pk_bf16_f32 v91, v84, v85
	v_cvt_pk_bf16_f32 v92, v86, v87
	v_cvt_pk_bf16_f32 v93, v88, v89
	global_store_dwordx4 v48, v[90:93], s[22:23]
	s_add_u32 s22, s22, 0x1000
	s_addc_u32 s23, s23, 0
	s_add_i32 s0, s47, 0
	s_cmp_lt_i32 s0, s43
	s_cbranch_scc1 .Lpl_sk_11
	v_lshlrev_b32_e32 v82, 16, v66
	v_and_b32_e32 v83, 0xffff0000, v66
	v_lshlrev_b32_e32 v84, 16, v67
	v_and_b32_e32 v85, 0xffff0000, v67
	v_lshlrev_b32_e32 v86, 16, v68
	v_and_b32_e32 v87, 0xffff0000, v68
	v_lshlrev_b32_e32 v88, 16, v69
	v_and_b32_e32 v89, 0xffff0000, v69
	v_pk_add_f32 v[32:33], v[32:33], v[82:83] neg_lo:[0,1] neg_hi:[0,1]
	v_pk_add_f32 v[34:35], v[34:35], v[84:85] neg_lo:[0,1] neg_hi:[0,1]
	v_pk_add_f32 v[36:37], v[36:37], v[86:87] neg_lo:[0,1] neg_hi:[0,1]
	v_pk_add_f32 v[38:39], v[38:39], v[88:89] neg_lo:[0,1] neg_hi:[0,1]
.Lpl_sk_11:
	s_add_i32 s0, s47, 2
	s_min_i32 s0, s0, s41
	v_cvt_f32_u32_e32 v98, s0
	v_div_scale_f32 v99, s[10:11], v98, v98, 1.0
	v_rcp_f32_e32 v100, v99
	s_nop 0
	v_fma_f32 v101, -v99, v100, 1.0
	v_fmac_f32_e32 v100, v101, v100
	v_div_scale_f32 v101, vcc, 1.0, v98, 1.0
	v_mul_f32_e32 v102, v101, v100
	v_fma_f32 v103, -v99, v102, v101
	v_fmac_f32_e32 v102, v103, v100
	v_fma_f32 v99, -v99, v102, v101
	v_div_fmas_f32 v99, v99, v100, v102
	v_div_fixup_f32 v94, v99, v98, 1.0
	v_mov_b32_e32 v95, v94
	v_lshlrev_b32_e32 v40, 16, v54
	v_and_b32_e32 v41, 0xffff0000, v54
	v_lshlrev_b32_e32 v42, 16, v55
	v_and_b32_e32 v43, 0xffff0000, v55
	v_lshlrev_b32_e32 v44, 16, v56
	v_and_b32_e32 v45, 0xffff0000, v56
	v_lshlrev_b32_e32 v46, 16, v57
	v_and_b32_e32 v47, 0xffff0000, v57
	v_pk_add_f32 v[32:33], v[32:33], v[40:41]
	v_pk_add_f32 v[34:35], v[34:35], v[42:43]
	v_pk_add_f32 v[36:37], v[36:37], v[44:45]
	v_pk_add_f32 v[38:39], v[38:39], v[46:47]
	v_pk_fma_f32 v[82:83], v[32:33], v[94:95], v[40:41] neg_lo:[0,0,1] neg_hi:[0,0,1]
	v_pk_fma_f32 v[84:85], v[34:35], v[94:95], v[42:43] neg_lo:[0,0,1] neg_hi:[0,0,1]
	v_pk_fma_f32 v[86:87], v[36:37], v[94:95], v[44:45] neg_lo:[0,0,1] neg_hi:[0,0,1]
	v_pk_fma_f32 v[88:89], v[38:39], v[94:95], v[46:47] neg_lo:[0,0,1] neg_hi:[0,0,1]
	v_cvt_pk_bf16_f32 v90, v82, v83
	v_cvt_pk_bf16_f32 v91, v84, v85
	v_cvt_pk_bf16_f32 v92, v86, v87
	v_cvt_pk_bf16_f32 v93, v88, v89
	global_store_dwordx4 v48, v[90:93], s[22:23]
	s_add_u32 s22, s22, 0x1000
	s_addc_u32 s23, s23, 0
	s_add_i32 s0, s47, 1
	s_cmp_lt_i32 s0, s43
	s_cbranch_scc1 .Lpl_sk_12
	v_lshlrev_b32_e32 v82, 16, v70
	v_and_b32_e32 v83, 0xffff0000, v70
	v_lshlrev_b32_e32 v84, 16, v71
	v_and_b32_e32 v85, 0xffff0000, v71
	v_lshlrev_b32_e32 v86, 16, v72
	v_and_b32_e32 v87, 0xffff0000, v72
	v_lshlrev_b32_e32 v88, 16, v73
	v_and_b32_e32 v89, 0xffff0000, v73
	v_pk_add_f32 v[32:33], v[32:33], v[82:83] neg_lo:[0,1] neg_hi:[0,1]
	v_pk_add_f32 v[34:35], v[34:35], v[84:85] neg_lo:[0,1] neg_hi:[0,1]
	v_pk_add_f32 v[36:37], v[36:37], v[86:87] neg_lo:[0,1] neg_hi:[0,1]
	v_pk_add_f32 v[38:39], v[38:39], v[88:89] neg_lo:[0,1] neg_hi:[0,1]
.Lpl_sk_12:
	s_add_i32 s0, s47, 3
	s_min_i32 s0, s0, s41
	v_cvt_f32_u32_e32 v98, s0
	v_div_scale_f32 v99, s[10:11], v98, v98, 1.0
	v_rcp_f32_e32 v100, v99
	s_nop 0
	v_fma_f32 v101, -v99, v100, 1.0
	v_fmac_f32_e32 v100, v101, v100
	v_div_scale_f32 v101, vcc, 1.0, v98, 1.0
	v_mul_f32_e32 v102, v101, v100
	v_fma_f32 v103, -v99, v102, v101
	v_fmac_f32_e32 v102, v103, v100
	v_fma_f32 v99, -v99, v102, v101
	v_div_fmas_f32 v99, v99, v100, v102
	v_div_fixup_f32 v94, v99, v98, 1.0
	v_mov_b32_e32 v95, v94
	v_lshlrev_b32_e32 v40, 16, v58
	v_and_b32_e32 v41, 0xffff0000, v58
	v_lshlrev_b32_e32 v42, 16, v59
	v_and_b32_e32 v43, 0xffff0000, v59
	v_lshlrev_b32_e32 v44, 16, v60
	v_and_b32_e32 v45, 0xffff0000, v60
	v_lshlrev_b32_e32 v46, 16, v61
	v_and_b32_e32 v47, 0xffff0000, v61
	v_pk_add_f32 v[32:33], v[32:33], v[40:41]
	v_pk_add_f32 v[34:35], v[34:35], v[42:43]
	v_pk_add_f32 v[36:37], v[36:37], v[44:45]
	v_pk_add_f32 v[38:39], v[38:39], v[46:47]
	v_pk_fma_f32 v[82:83], v[32:33], v[94:95], v[40:41] neg_lo:[0,0,1] neg_hi:[0,0,1]
	v_pk_fma_f32 v[84:85], v[34:35], v[94:95], v[42:43] neg_lo:[0,0,1] neg_hi:[0,0,1]
	v_pk_fma_f32 v[86:87], v[36:37], v[94:95], v[44:45] neg_lo:[0,0,1] neg_hi:[0,0,1]
	v_pk_fma_f32 v[88:89], v[38:39], v[94:95], v[46:47] neg_lo:[0,0,1] neg_hi:[0,0,1]
	v_cvt_pk_bf16_f32 v90, v82, v83
	v_cvt_pk_bf16_f32 v91, v84, v85
	v_cvt_pk_bf16_f32 v92, v86, v87
	v_cvt_pk_bf16_f32 v93, v88, v89
	global_store_dwordx4 v48, v[90:93], s[22:23]
	s_add_u32 s22, s22, 0x1000
	s_addc_u32 s23, s23, 0
	s_add_i32 s0, s47, 2
	s_cmp_lt_i32 s0, s43
	s_cbranch_scc1 .Lpl_sk_13
	v_lshlrev_b32_e32 v82, 16, v74
	v_and_b32_e32 v83, 0xffff0000, v74
	v_lshlrev_b32_e32 v84, 16, v75
	v_and_b32_e32 v85, 0xffff0000, v75
	v_lshlrev_b32_e32 v86, 16, v76
	v_and_b32_e32 v87, 0xffff0000, v76
	v_lshlrev_b32_e32 v88, 16, v77
	v_and_b32_e32 v89, 0xffff0000, v77
	v_pk_add_f32 v[32:33], v[32:33], v[82:83] neg_lo:[0,1] neg_hi:[0,1]
	v_pk_add_f32 v[34:35], v[34:35], v[84:85] neg_lo:[0,1] neg_hi:[0,1]
	v_pk_add_f32 v[36:37], v[36:37], v[86:87] neg_lo:[0,1] neg_hi:[0,1]
	v_pk_add_f32 v[38:39], v[38:39], v[88:89] neg_lo:[0,1] neg_hi:[0,1]
.Lpl_sk_13:
	s_add_i32 s0, s47, 4
	s_min_i32 s0, s0, s41
	v_cvt_f32_u32_e32 v98, s0
	v_div_scale_f32 v99, s[10:11], v98, v98, 1.0
	v_rcp_f32_e32 v100, v99
	s_nop 0
	v_fma_f32 v101, -v99, v100, 1.0
	v_fmac_f32_e32 v100, v101, v100
	v_div_scale_f32 v101, vcc, 1.0, v98, 1.0
	v_mul_f32_e32 v102, v101, v100
	v_fma_f32 v103, -v99, v102, v101
	v_fmac_f32_e32 v102, v103, v100
	v_fma_f32 v99, -v99, v102, v101
	v_div_fmas_f32 v99, v99, v100, v102
	v_div_fixup_f32 v94, v99, v98, 1.0
	v_mov_b32_e32 v95, v94
	v_lshlrev_b32_e32 v40, 16, v62
	v_and_b32_e32 v41, 0xffff0000, v62
	v_lshlrev_b32_e32 v42, 16, v63
	v_and_b32_e32 v43, 0xffff0000, v63
	v_lshlrev_b32_e32 v44, 16, v64
	v_and_b32_e32 v45, 0xffff0000, v64
	v_lshlrev_b32_e32 v46, 16, v65
	v_and_b32_e32 v47, 0xffff0000, v65
	v_pk_add_f32 v[32:33], v[32:33], v[40:41]
	v_pk_add_f32 v[34:35], v[34:35], v[42:43]
	v_pk_add_f32 v[36:37], v[36:37], v[44:45]
	v_pk_add_f32 v[38:39], v[38:39], v[46:47]
	v_pk_fma_f32 v[82:83], v[32:33], v[94:95], v[40:41] neg_lo:[0,0,1] neg_hi:[0,0,1]
	v_pk_fma_f32 v[84:85], v[34:35], v[94:95], v[42:43] neg_lo:[0,0,1] neg_hi:[0,0,1]
	v_pk_fma_f32 v[86:87], v[36:37], v[94:95], v[44:45] neg_lo:[0,0,1] neg_hi:[0,0,1]
	v_pk_fma_f32 v[88:89], v[38:39], v[94:95], v[46:47] neg_lo:[0,0,1] neg_hi:[0,0,1]
	v_cvt_pk_bf16_f32 v90, v82, v83
	v_cvt_pk_bf16_f32 v91, v84, v85
	v_cvt_pk_bf16_f32 v92, v86, v87
	v_cvt_pk_bf16_f32 v93, v88, v89
	global_store_dwordx4 v48, v[90:93], s[22:23]
	s_add_u32 s22, s22, 0x1000
	s_addc_u32 s23, s23, 0
	s_add_i32 s0, s47, 3
	s_cmp_lt_i32 s0, s43
	s_cbranch_scc1 .Lpl_sk_14
	v_lshlrev_b32_e32 v82, 16, v78
	v_and_b32_e32 v83, 0xffff0000, v78
	v_lshlrev_b32_e32 v84, 16, v79
	v_and_b32_e32 v85, 0xffff0000, v79
	v_lshlrev_b32_e32 v86, 16, v80
	v_and_b32_e32 v87, 0xffff0000, v80
	v_lshlrev_b32_e32 v88, 16, v81
	v_and_b32_e32 v89, 0xffff0000, v81
	v_pk_add_f32 v[32:33], v[32:33], v[82:83] neg_lo:[0,1] neg_hi:[0,1]
	v_pk_add_f32 v[34:35], v[34:35], v[84:85] neg_lo:[0,1] neg_hi:[0,1]
	v_pk_add_f32 v[36:37], v[36:37], v[86:87] neg_lo:[0,1] neg_hi:[0,1]
	v_pk_add_f32 v[38:39], v[38:39], v[88:89] neg_lo:[0,1] neg_hi:[0,1]
.Lpl_sk_14:
	s_add_i32 s46, s40, 12
	s_add_i32 s0, s48, -4
	s_min_i32 s46, s46, s0
	s_add_i32 s0, s42, s46
	s_lshl_b32 s0, s0, 13
	s_add_u32 s8, s4, s0
	s_addc_u32 s9, s5, 0
	global_load_dwordx4 v[50:53], v48, s[8:9]
	s_add_u32 s8, s8, 0x2000
	s_addc_u32 s9, s9, 0
	global_load_dwordx4 v[54:57], v48, s[8:9]
	s_add_u32 s8, s8, 0x2000
	s_addc_u32 s9, s9, 0
	global_load_dwordx4 v[58:61], v48, s[8:9]
	s_add_u32 s8, s8, 0x2000
	s_addc_u32 s9, s9, 0
	global_load_dwordx4 v[62:65], v48, s[8:9]
	s_sub_i32 s1, s46, s43
	s_add_i32 s0, s1, 0
	s_max_i32 s0, s0, 0
	s_add_i32 s0, s0, s42
	s_lshl_b32 s0, s0, 13
	s_add_u32 s10, s4, s0
	s_addc_u32 s11, s5, 0
	global_load_dwordx4 v[66:69], v48, s[10:11]
	s_add_i32 s0, s1, 1
	s_max_i32 s0, s0, 0
	s_add_i32 s0, s0, s42
	s_lshl_b32 s0, s0, 13
	s_add_u32 s10, s4, s0
	s_addc_u32 s11, s5, 0
	global_load_dwordx4 v[70:73], v48, s[10:11]
	s_add_i32 s0, s1, 2
	s_max_i32 s0, s0, 0
	s_add_i32 s0, s0, s42
	s_lshl_b32 s0, s0, 13
	s_add_u32 s10, s4, s0
	s_addc_u32 s11, s5, 0
	global_load_dwordx4 v[74:77], v48, s[10:11]
	s_add_i32 s0, s1, 3
	s_max_i32 s0, s0, 0
	s_add_i32 s0, s0, s42
	s_lshl_b32 s0, s0, 13
	s_add_u32 s10, s4, s0
	s_addc_u32 s11, s5, 0
	global_load_dwordx4 v[78:81], v48, s[10:11]
	s_waitcnt vmcnt(12)
	s_add_i32 s40, s40, 8
	s_cmp_lt_i32 s40, s48
	s_cbranch_scc1 .Lpl_loop_6
	s_cmp_lt_u32 s49, 0x8000
	s_cbranch_scc0 .Lpl_done_15
	s_waitcnt vmcnt(0)
	s_lshr_b32 s1, s49, 8
	s_lshl_b32 s0, s1, 3
	s_add_i32 s42, s0, 0x4000
	s_add_i32 s0, s21, s1
	s_mul_i32 s47, s0, 15
	s_lshl_b32 s0, s42, 12
	s_add_u32 s22, s70, s0
	s_addc_u32 s23, s71, 0
	s_lshl_b32 s0, s42, 13
	s_add_u32 s8, s4, s0
	s_addc_u32 s9, s5, 0
	global_load_dwordx4 v[0:3], v48, s[8:9]
	s_add_u32 s8, s8, 0x2000
	s_addc_u32 s9, s9, 0
	global_load_dwordx4 v[4:7], v48, s[8:9]
	s_add_u32 s8, s8, 0x2000
	s_addc_u32 s9, s9, 0
	global_load_dwordx4 v[8:11], v48, s[8:9]
	s_add_u32 s8, s8, 0x2000
	s_addc_u32 s9, s9, 0
	global_load_dwordx4 v[12:15], v48, s[8:9]
	s_add_u32 s8, s8, 0x2000
	s_addc_u32 s9, s9, 0
	global_load_dwordx4 v[16:19], v48, s[8:9]
	s_add_u32 s8, s8, 0x2000
	s_addc_u32 s9, s9, 0
	global_load_dwordx4 v[20:23], v48, s[8:9]
	s_add_u32 s8, s8, 0x2000
	s_addc_u32 s9, s9, 0
	global_load_dwordx4 v[24:27], v48, s[8:9]
	s_add_u32 s8, s8, 0x2000
	s_addc_u32 s9, s9, 0
	global_load_dwordx4 v[28:31], v48, s[8:9]
	v_mov_b32_e32 v32, 0
	v_mov_b32_e32 v33, 0
	v_mov_b32_e32 v34, 0
	v_mov_b32_e32 v35, 0
	v_mov_b32_e32 v36, 0
	v_mov_b32_e32 v37, 0
	v_mov_b32_e32 v38, 0
	v_mov_b32_e32 v39, 0
	s_mov_b32 s40, 1
.Lpl_sw_16:
	s_add_i32 s1, s40, 0
	s_cmp_gt_i32 s1, s43
	s_cbranch_scc1 .Lpl_swl_17
	s_sub_i32 s1, 15, s1
	s_add_i32 s0, s47, s1
	s_lshl_b32 s0, s0, 13
	s_add_u32 s10, s36, s0
	s_addc_u32 s11, s37, 0
	global_load_dwordx4 v[50:53], v114, s[10:11]
	global_load_dwordx4 v[54:57], v114, s[10:11] offset:16
.Lpl_swl_17:
	s_add_i32 s1, s40, 1
	s_cmp_gt_i32 s1, s43
	s_cbranch_scc1 .Lpl_swl_18
	s_sub_i32 s1, 15, s1
	s_add_i32 s0, s47, s1
	s_lshl_b32 s0, s0, 13
	s_add_u32 s10, s36, s0
	s_addc_u32 s11, s37, 0
	global_load_dwordx4 v[58:61], v114, s[10:11]
	global_load_dwordx4 v[62:65], v114, s[10:11] offset:16
.Lpl_swl_18:
	s_add_i32 s1, s40, 2
	s_cmp_gt_i32 s1, s43
	s_cbranch_scc1 .Lpl_swl_19
	s_sub_i32 s1, 15, s1
	s_add_i32 s0, s47, s1
	s_lshl_b32 s0, s0, 13
	s_add_u32 s10, s36, s0
	s_addc_u32 s11, s37, 0
	global_load_dwordx4 v[66:69], v114, s[10:11]
	global_load_dwordx4 v[70:73], v114, s[10:11] offset:16
.Lpl_swl_19:
	s_add_i32 s1, s40, 3
	s_cmp_gt_i32 s1, s43
	s_cbranch_scc1 .Lpl_swl_20
	s_sub_i32 s1, 15, s1
	s_add_i32 s0, s47, s1
	s_lshl_b32 s0, s0, 13
	s_add_u32 s10, s36, s0
	s_addc_u32 s11, s37, 0
	global_load_dwordx4 v[74:77], v114, s[10:11]
	global_load_dwordx4 v[78:81], v114, s[10:11] offset:16

.Lpl_swa_24:
	s_add_i32 s40, s40, 4
	s_cmp_le_i32 s40, s43
	s_cbranch_scc1 .Lpl_sw_16
	v_cvt_f32_u32_e32 v98, s41
	v_div_scale_f32 v99, s[10:11], v98, v98, 1.0
	v_rcp_f32_e32 v100, v99
	s_nop 0
	v_fma_f32 v101, -v99, v100, 1.0
	v_fmac_f32_e32 v100, v101, v100
	v_div_scale_f32 v101, vcc, 1.0, v98, 1.0
	v_mul_f32_e32 v102, v101, v100
	v_fma_f32 v103, -v99, v102, v101
	v_fmac_f32_e32 v102, v103, v100
	v_fma_f32 v99, -v99, v102, v101
	v_div_fmas_f32 v99, v99, v100, v102
	v_div_fixup_f32 v94, v99, v98, 1.0
	v_mov_b32_e32 v95, v94
	s_cmp_lt_i32 s43, 1
	s_cbranch_scc1 .Lpl_of_25
	s_sub_i32 s1, 15, s43
	s_add_i32 s0, s47, s1
	s_lshl_b32 s0, s0, 13
	s_add_u32 s10, s36, s0
	s_addc_u32 s11, s37, 0
	global_load_dwordx4 v[50:53], v114, s[10:11]
	global_load_dwordx4 v[54:57], v114, s[10:11] offset:16
	s_branch .Lpl_oe_26

.Lpl_oe_26:
	s_cmp_lt_i32 s43, 2
	s_cbranch_scc1 .Lpl_of_27
	s_sub_i32 s1, 16, s43
	s_add_i32 s0, s47, s1
	s_lshl_b32 s0, s0, 13
	s_add_u32 s10, s36, s0
	s_addc_u32 s11, s37, 0
	global_load_dwordx4 v[58:61], v114, s[10:11]
	global_load_dwordx4 v[62:65], v114, s[10:11] offset:16
	s_branch .Lpl_oe_28

.Lpl_oe_28:
	s_cmp_lt_i32 s43, 3
	s_cbranch_scc1 .Lpl_of_29
	s_sub_i32 s1, 17, s43
	s_add_i32 s0, s47, s1
	s_lshl_b32 s0, s0, 13
	s_add_u32 s10, s36, s0
	s_addc_u32 s11, s37, 0
	global_load_dwordx4 v[66:69], v114, s[10:11]
	global_load_dwordx4 v[70:73], v114, s[10:11] offset:16
	s_branch .Lpl_oe_30

.Lpl_oe_30:
	s_cmp_lt_i32 s43, 4
	s_cbranch_scc1 .Lpl_of_31
	s_sub_i32 s1, 18, s43
	s_add_i32 s0, s47, s1
	s_lshl_b32 s0, s0, 13
	s_add_u32 s10, s36, s0
	s_addc_u32 s11, s37, 0
	global_load_dwordx4 v[74:77], v114, s[10:11]
	global_load_dwordx4 v[78:81], v114, s[10:11] offset:16
	s_branch .Lpl_oe_32

.Lpl_se_40:
	s_cmp_lt_i32 s43, 5
	s_cbranch_scc1 .Lpl_of_41
	s_sub_i32 s1, 19, s43
	s_add_i32 s0, s47, s1
	s_lshl_b32 s0, s0, 13
	s_add_u32 s10, s36, s0
	s_addc_u32 s11, s37, 0
	global_load_dwordx4 v[50:53], v114, s[10:11]
	global_load_dwordx4 v[54:57], v114, s[10:11] offset:16
	s_branch .Lpl_oe_42

.Lpl_oe_42:
	s_cmp_lt_i32 s43, 6
	s_cbranch_scc1 .Lpl_of_43
	s_sub_i32 s1, 20, s43
	s_add_i32 s0, s47, s1
	s_lshl_b32 s0, s0, 13
	s_add_u32 s10, s36, s0
	s_addc_u32 s11, s37, 0
	global_load_dwordx4 v[58:61], v114, s[10:11]
	global_load_dwordx4 v[62:65], v114, s[10:11] offset:16
	s_branch .Lpl_oe_44

.Lpl_oe_44:
	s_cmp_lt_i32 s43, 7
	s_cbranch_scc1 .Lpl_of_45
	s_sub_i32 s1, 21, s43
	s_add_i32 s0, s47, s1
	s_lshl_b32 s0, s0, 13
	s_add_u32 s10, s36, s0
	s_addc_u32 s11, s37, 0
	global_load_dwordx4 v[66:69], v114, s[10:11]
	global_load_dwordx4 v[70:73], v114, s[10:11] offset:16
	s_branch .Lpl_oe_46

.Lpl_oe_46:
	s_cmp_lt_i32 s43, 8
	s_cbranch_scc1 .Lpl_of_47
	s_sub_i32 s1, 22, s43
	s_add_i32 s0, s47, s1
	s_lshl_b32 s0, s0, 13
	s_add_u32 s10, s36, s0
	s_addc_u32 s11, s37, 0
	global_load_dwordx4 v[74:77], v114, s[10:11]
	global_load_dwordx4 v[78:81], v114, s[10:11] offset:16
	s_branch .Lpl_oe_48
